# version 63 plus ph_post context rows batched (eight row loads in flight), without the first-row-early change
# speedup vs baseline: 1.0021x; 1.0021x over previous
.LBB0_316:
	s_cmp_lt_i32 s72, 5
	s_cselect_b64 s[6:7], -1, 0
	s_and_b64 s[4:5], s[6:7], s[4:5]
	s_andn2_b64 vcc, exec, s[4:5]
	s_cbranch_vccnz .LBB0_326
	s_lshl_b32 s3, s2, 3
	s_add_i32 s16, s96, s3
	s_cmpk_gt_i32 s16, 0x2fff
	s_cbranch_scc1 .LBB0_326
	v_lshlrev_b32_e32 v1, 3, v0
	v_and_b32_e32 v2, 56, v1
	v_or_b32_e32 v4, 1, v2
	v_cvt_f32_ubyte0_e32 v4, v4
	v_mul_f32_e32 v4, 0xbe549a78, v4
	v_exp_f32_e32 v62, v4
	v_or_b32_e32 v4, 2, v2
	v_cvt_f32_ubyte0_e32 v4, v4
	v_mul_f32_e32 v4, 0xbe549a78, v4
	v_exp_f32_e32 v63, v4
	v_or_b32_e32 v4, 3, v2
	v_cvt_f32_ubyte0_e32 v4, v4
	v_mul_f32_e32 v4, 0xbe549a78, v4
	v_exp_f32_e32 v64, v4
	v_or_b32_e32 v4, 4, v2
	v_cvt_f32_ubyte0_e32 v4, v4
	v_mul_f32_e32 v4, 0xbe549a78, v4
	v_exp_f32_e32 v65, v4
	v_or_b32_e32 v4, 5, v2
	v_cvt_f32_ubyte0_e32 v4, v4
	v_and_b32_e32 v3, 24, v1
	v_and_b32_e32 v1, 8, v0
	v_mul_f32_e32 v4, 0xbe549a78, v4
	v_cmp_eq_u32_e64 s[4:5], 0, v1
	v_cvt_f32_ubyte0_e32 v1, v2
	v_exp_f32_e32 v66, v4
	v_or_b32_e32 v4, 6, v2
	v_or_b32_e32 v2, 7, v2
	v_cvt_f32_ubyte0_e32 v2, v2
	v_mul_f32_e32 v2, 0xbe549a78, v2
	v_exp_f32_e32 v68, v2
	v_and_b32_e32 v2, 4, v0
	v_cmp_eq_u32_e64 s[6:7], 0, v2
	v_cvt_f32_ubyte0_e32 v2, v3
	v_mul_f32_e32 v2, 0xbed49a78, v2
	v_exp_f32_e32 v69, v2
	v_or_b32_e32 v2, 1, v3
	v_cvt_f32_ubyte0_e32 v2, v2
	v_mul_f32_e32 v2, 0xbed49a78, v2
	v_exp_f32_e32 v70, v2
	v_or_b32_e32 v2, 2, v3
	v_cvt_f32_ubyte0_e32 v2, v2
	v_mul_f32_e32 v2, 0xbed49a78, v2
	v_exp_f32_e32 v71, v2
	v_or_b32_e32 v2, 3, v3
	v_cvt_f32_ubyte0_e32 v2, v2
	v_mul_f32_e32 v2, 0xbed49a78, v2
	v_exp_f32_e32 v72, v2
	v_or_b32_e32 v2, 4, v3
	v_cvt_f32_ubyte0_e32 v2, v2
	v_mul_f32_e32 v2, 0xbed49a78, v2
	v_exp_f32_e32 v73, v2
	v_or_b32_e32 v2, 5, v3
	v_cvt_f32_ubyte0_e32 v2, v2
	v_mul_f32_e32 v2, 0xbed49a78, v2
	v_exp_f32_e32 v74, v2
	v_or_b32_e32 v2, 6, v3
	v_cvt_f32_ubyte0_e32 v2, v2
	v_mul_f32_e32 v2, 0xbed49a78, v2
	s_ashr_i32 s17, s16, 31
	s_lshl_b32 s42, s33, 3
	v_exp_f32_e32 v75, v2
	v_or_b32_e32 v2, 7, v3
	s_lshl_b64 s[10:11], s[16:17], 11
	v_cvt_f32_ubyte0_e32 v2, v2
	s_add_u32 s10, s68, s10
	v_mul_f32_e32 v2, 0xbed49a78, v2
	v_lshlrev_b32_e32 v38, 5, v174
	v_mov_b32_e32 v39, 0
	s_addc_u32 s11, s69, s11
	v_cvt_f32_ubyte0_e32 v4, v4
	v_exp_f32_e32 v76, v2
	v_lshl_add_u64 v[2:3], s[10:11], 0, v[38:39]
	s_mov_b64 s[10:11], 0xc000000
	s_ashr_i32 s43, s42, 31
	v_mul_f32_e32 v4, 0xbe549a78, v4
	v_lshl_add_u64 v[40:41], v[2:3], 0, s[10:11]
	s_lshl_b64 s[44:45], s[42:43], 11
	s_mul_i32 s10, s16, 0x9800
	v_and_b32_e32 v2, 7, v0
	v_exp_f32_e32 v67, v4
	s_add_u32 s46, s70, s10
	v_lshlrev_b32_e32 v2, 4, v2
	v_lshlrev_b32_e32 v3, 5, v0
	s_movk_i32 s10, 0x700
	v_and_b32_e32 v4, 3, v0
	v_and_or_b32 v44, v3, s10, v2
	v_lshlrev_b32_e32 v4, 4, v4
	s_movk_i32 s10, 0x780
	v_mul_f32_e32 v1, 0xbe549a78, v1
	v_and_or_b32 v46, v3, s10, v4
	v_or_b32_e32 v5, 0x800, v38
	s_movk_i32 s10, 0xf00
	v_exp_f32_e32 v1, v1
	v_and_or_b32 v48, v5, s10, v2
	s_movk_i32 s10, 0x380
	v_and_or_b32 v50, v3, s10, v4
	s_movk_i32 s10, 0xf80
	v_mov_b32_e32 v2, 0x800
	s_mul_hi_i32 s3, s16, 0x9800
	v_bitop3_b32 v2, v38, s10, v2 bitop3:0xc8
	v_cmp_gt_u32_e64 s[8:9], 32, v174
	v_lshlrev_b32_e32 v42, 4, v174
	v_mov_b32_e32 v43, v39
	s_addc_u32 s47, s71, s3
	s_mul_i32 s3, s33, 0x4c000
	s_mul_hi_i32 s17, s42, 0x9800
	v_mov_b32_e32 v45, v39
	v_mov_b32_e32 v47, v39
	v_mov_b32_e32 v49, v39
	v_mov_b32_e32 v51, v39
	v_or_b32_e32 v38, v2, v4
	s_mov_b32 s24, 0x1ec00000
	s_mov_b32 s25, 0x1ec01000
	s_mov_b32 s30, 0x1ec04000
	s_mov_b32 s31, 0x1ec05000
	s_mov_b32 s60, 0x3e0293ee
	s_cmp_lg_u32 s33, 0x100
	s_cbranch_scc1 .Lpost_skip
	s_add_u32 s10, s46, 0x1ec05000
	s_addc_u32 s11, s47, 0
	global_load_dwordx4 v[88:91], v42, s[10:11]
	global_load_dwordx4 v[92:95], v42, s[10:11] offset:1024
	s_add_u32 s10, s46, 0x23805000
	s_addc_u32 s11, s47, 0
	global_load_dwordx4 v[96:99], v42, s[10:11]
	global_load_dwordx4 v[100:103], v42, s[10:11] offset:1024
	s_add_u32 s10, s46, 0x28405000
	s_addc_u32 s11, s47, 0
	global_load_dwordx4 v[104:107], v42, s[10:11]
	global_load_dwordx4 v[108:111], v42, s[10:11] offset:1024
	s_add_u32 s10, s46, 0x2d005000
	s_addc_u32 s11, s47, 0
	global_load_dwordx4 v[112:115], v42, s[10:11]
	global_load_dwordx4 v[116:119], v42, s[10:11] offset:1024
	s_waitcnt vmcnt(6)
	s_mov_b32 s12, 0x0
	s_mov_b32 s13, 0
	v_lshl_add_u64 v[152:153], s[12:13], 0, v[40:41]
	s_mov_b32 s12, 0x1000000
	v_lshl_add_u64 v[154:155], s[12:13], 0, v[40:41]
	v_lshlrev_b32_e32 v120, 16, v88
	v_and_b32_e32 v121, 0xffff0000, v88
	v_lshlrev_b32_e32 v122, 16, v89
	v_and_b32_e32 v123, 0xffff0000, v89
	v_lshlrev_b32_e32 v124, 16, v90
	v_and_b32_e32 v125, 0xffff0000, v90
	v_lshlrev_b32_e32 v126, 16, v91
	v_and_b32_e32 v127, 0xffff0000, v91
	v_lshlrev_b32_e32 v128, 16, v92
	v_and_b32_e32 v129, 0xffff0000, v92
	v_lshlrev_b32_e32 v130, 16, v93
	v_and_b32_e32 v131, 0xffff0000, v93
	v_lshlrev_b32_e32 v132, 16, v94
	v_and_b32_e32 v133, 0xffff0000, v94
	v_lshlrev_b32_e32 v134, 16, v95
	v_and_b32_e32 v135, 0xffff0000, v95
	global_store_dwordx4 v[152:153], v[120:123], off
	global_store_dwordx4 v[152:153], v[124:127], off offset:16
	global_store_dwordx4 v[154:155], v[128:131], off
	global_store_dwordx4 v[154:155], v[132:135], off offset:16
	s_nop 1
	s_waitcnt vmcnt(8)
	s_mov_b32 s12, 0x400000
	s_mov_b32 s13, 0
	v_lshl_add_u64 v[152:153], s[12:13], 0, v[40:41]
	s_mov_b32 s12, 0x1400000
	v_lshl_add_u64 v[154:155], s[12:13], 0, v[40:41]
	v_lshlrev_b32_e32 v136, 16, v96
	v_and_b32_e32 v137, 0xffff0000, v96
	v_lshlrev_b32_e32 v138, 16, v97
	v_and_b32_e32 v139, 0xffff0000, v97
	v_lshlrev_b32_e32 v140, 16, v98
	v_and_b32_e32 v141, 0xffff0000, v98
	v_lshlrev_b32_e32 v142, 16, v99
	v_and_b32_e32 v143, 0xffff0000, v99
	v_lshlrev_b32_e32 v144, 16, v100
	v_and_b32_e32 v145, 0xffff0000, v100
	v_lshlrev_b32_e32 v146, 16, v101
	v_and_b32_e32 v147, 0xffff0000, v101
	v_lshlrev_b32_e32 v148, 16, v102
	v_and_b32_e32 v149, 0xffff0000, v102
	v_lshlrev_b32_e32 v150, 16, v103
	v_and_b32_e32 v151, 0xffff0000, v103
	global_store_dwordx4 v[152:153], v[136:139], off
	global_store_dwordx4 v[152:153], v[140:143], off offset:16
	global_store_dwordx4 v[154:155], v[144:147], off
	global_store_dwordx4 v[154:155], v[148:151], off offset:16
	s_nop 1
	s_waitcnt vmcnt(10)
	s_mov_b32 s12, 0x800000
	s_mov_b32 s13, 0
	v_lshl_add_u64 v[152:153], s[12:13], 0, v[40:41]
	s_mov_b32 s12, 0x1800000
	v_lshl_add_u64 v[154:155], s[12:13], 0, v[40:41]
	v_lshlrev_b32_e32 v120, 16, v104
	v_and_b32_e32 v121, 0xffff0000, v104
	v_lshlrev_b32_e32 v122, 16, v105
	v_and_b32_e32 v123, 0xffff0000, v105
	v_lshlrev_b32_e32 v124, 16, v106
	v_and_b32_e32 v125, 0xffff0000, v106
	v_lshlrev_b32_e32 v126, 16, v107
	v_and_b32_e32 v127, 0xffff0000, v107
	v_lshlrev_b32_e32 v128, 16, v108
	v_and_b32_e32 v129, 0xffff0000, v108
	v_lshlrev_b32_e32 v130, 16, v109
	v_and_b32_e32 v131, 0xffff0000, v109
	v_lshlrev_b32_e32 v132, 16, v110
	v_and_b32_e32 v133, 0xffff0000, v110
	v_lshlrev_b32_e32 v134, 16, v111
	v_and_b32_e32 v135, 0xffff0000, v111
	global_store_dwordx4 v[152:153], v[120:123], off
	global_store_dwordx4 v[152:153], v[124:127], off offset:16
	global_store_dwordx4 v[154:155], v[128:131], off
	global_store_dwordx4 v[154:155], v[132:135], off offset:16
	s_nop 1
	s_waitcnt vmcnt(12)
	s_mov_b32 s12, 0xc00000
	s_mov_b32 s13, 0
	v_lshl_add_u64 v[152:153], s[12:13], 0, v[40:41]
	s_mov_b32 s12, 0x1c00000
	v_lshl_add_u64 v[154:155], s[12:13], 0, v[40:41]
	v_lshlrev_b32_e32 v136, 16, v112
	v_and_b32_e32 v137, 0xffff0000, v112
	v_lshlrev_b32_e32 v138, 16, v113
	v_and_b32_e32 v139, 0xffff0000, v113
	v_lshlrev_b32_e32 v140, 16, v114
	v_and_b32_e32 v141, 0xffff0000, v114
	v_lshlrev_b32_e32 v142, 16, v115
	v_and_b32_e32 v143, 0xffff0000, v115
	v_lshlrev_b32_e32 v144, 16, v116
	v_and_b32_e32 v145, 0xffff0000, v116
	v_lshlrev_b32_e32 v146, 16, v117
	v_and_b32_e32 v147, 0xffff0000, v117
	v_lshlrev_b32_e32 v148, 16, v118
	v_and_b32_e32 v149, 0xffff0000, v118
	v_lshlrev_b32_e32 v150, 16, v119
	v_and_b32_e32 v151, 0xffff0000, v119
	global_store_dwordx4 v[152:153], v[136:139], off
	global_store_dwordx4 v[152:153], v[140:143], off offset:16
	global_store_dwordx4 v[154:155], v[144:147], off
	global_store_dwordx4 v[154:155], v[148:151], off offset:16
	s_nop 1
	s_lshl_b32 s12, s42, 2
	s_add_i32 s16, s16, s12
	s_add_u32 s46, s46, 0x13000000
	s_addc_u32 s47, s47, 0
	s_mov_b32 s12, 0x1000000
	s_mov_b32 s13, 0
	v_lshl_add_u64 v[40:41], s[12:13], 0, v[40:41]
.Lpost_skip:
	s_branch .LBB0_320
.LBB0_319:
	s_add_i32 s16, s16, s42
	s_add_u32 s46, s46, s3
	s_addc_u32 s47, s47, s17
	s_cmpk_lt_i32 s16, 0x3000
	v_lshl_add_u64 v[40:41], v[40:41], 0, s[44:45]
	s_cbranch_scc0 .LBB0_326
